# panel-local hand-off P3->P4 (L2-resident m tiles, grid barrier 3 removed)
# speedup vs baseline: 1.0258x; 1.0086x over previous
.LBB0_527:
	v_mov_b32_e32 v1, v222
	v_mov_b32_e32 v2, v197
	s_and_b64 vcc, exec, s[0:1]
	v_add_u32_e32 v132, s15, v2
	v_lshl_add_u32 v2, v1, 3, s47
	v_ashrrev_i32_e32 v3, 31, v2
	v_lshlrev_b64 v[2:3], 1, v[2:3]
	v_ashrrev_i32_e32 v133, 31, v132
	v_lshl_add_u64 v[134:135], s[4:5], 0, v[2:3]
	v_lshlrev_b64 v[136:137], 12, v[132:133]
	v_lshl_add_u64 v[136:137], v[134:135], 0, v[136:137]
	global_load_dwordx4 v[188:191], v[136:137], off
	global_load_dwordx4 v[192:195], v[136:137], off offset:256
	v_add_u32_e32 v232, 16, v132
	v_add_u32_e32 v186, 32, v132
	v_add_u32_e32 v184, 48, v132
	v_add_u32_e32 v182, 0x80, v132
	v_add_u32_e32 v180, 0x90, v132
	v_add_u32_e32 v178, 0xa0, v132
	v_add_u32_e32 v176, 0xb0, v132
	v_ashrrev_i32_e32 v233, 31, v232
	v_ashrrev_i32_e32 v187, 31, v186
	v_ashrrev_i32_e32 v185, 31, v184
	v_ashrrev_i32_e32 v183, 31, v182
	v_ashrrev_i32_e32 v181, 31, v180
	v_ashrrev_i32_e32 v179, 31, v178
	v_ashrrev_i32_e32 v177, 31, v176
	v_lshlrev_b64 v[234:235], 11, v[132:133]
	v_lshlrev_b64 v[132:133], 12, v[232:233]
	v_lshlrev_b64 v[136:137], 12, v[186:187]
	v_lshlrev_b64 v[138:139], 12, v[184:185]
	v_lshlrev_b64 v[140:141], 12, v[182:183]
	v_lshlrev_b64 v[142:143], 12, v[180:181]
	v_lshlrev_b64 v[144:145], 12, v[178:179]
	v_lshlrev_b64 v[146:147], 12, v[176:177]
	v_lshl_add_u64 v[132:133], v[134:135], 0, v[132:133]
	v_lshl_add_u64 v[136:137], v[134:135], 0, v[136:137]
	v_lshl_add_u64 v[138:139], v[134:135], 0, v[138:139]
	v_lshl_add_u64 v[140:141], v[134:135], 0, v[140:141]
	v_lshl_add_u64 v[142:143], v[134:135], 0, v[142:143]
	v_lshl_add_u64 v[236:237], v[134:135], 0, v[144:145]
	v_lshl_add_u64 v[134:135], v[134:135], 0, v[146:147]
	global_load_dwordx4 v[214:217], v[132:133], off
	global_load_dwordx4 v[218:221], v[132:133], off offset:256
	global_load_dwordx4 v[226:229], v[136:137], off
	global_load_dwordx4 v[172:175], v[136:137], off offset:256
	global_load_dwordx4 v[168:171], v[138:139], off
	global_load_dwordx4 v[164:167], v[138:139], off offset:256
	global_load_dwordx4 v[160:163], v[140:141], off
	global_load_dwordx4 v[156:159], v[140:141], off offset:256
	global_load_dwordx4 v[152:155], v[142:143], off
	global_load_dwordx4 v[148:151], v[142:143], off offset:256
	global_load_dwordx4 v[144:147], v[236:237], off
	s_nop 0
	global_load_dwordx4 v[140:143], v[236:237], off offset:256
	global_load_dwordx4 v[136:139], v[134:135], off
	s_nop 0
	global_load_dwordx4 v[132:135], v[134:135], off offset:256
	s_mov_b32 s25, s14
	s_mov_b32 s24, s16
	s_mov_b64 s[26:27], s[20:21]
	s_mov_b64 s[22:23], s[18:19]
	s_waitcnt vmcnt(0)
	v_lshlrev_b32_e32 v1, 16, v188
	v_and_b32_e32 v188, 0xffff0000, v188
	v_lshlrev_b32_e32 v196, 16, v189
	v_and_b32_e32 v189, 0xffff0000, v189
	v_lshlrev_b32_e32 v225, 16, v190
	v_max_f32_e32 v1, v1, v1
	v_max_f32_e32 v188, v188, v188
	v_max_f32_e32 v196, v196, v196
	v_max_f32_e32 v189, v189, v189
	v_max_f32_e32 v225, v225, v225
	v_max_f32_e32 v1, 0x219392ef, v1
	v_max_f32_e32 v188, 0x219392ef, v188
	v_max_f32_e32 v196, 0x219392ef, v196
	v_max_f32_e32 v189, 0x219392ef, v189
	v_max_f32_e32 v225, 0x219392ef, v225
	v_mul_f32_e32 v1, v128, v1
	v_mul_f32_e32 v128, v129, v188
	v_mul_f32_e32 v129, v130, v196
	v_mul_f32_e32 v130, v131, v189
	v_mul_f32_e32 v131, v124, v225
	v_cvt_pk_bf16_f32 v124, v1, v128
	v_lshlrev_b32_e32 v1, 16, v192
	v_max_f32_e32 v1, v1, v1
	v_max_f32_e32 v1, 0x219392ef, v1
	v_and_b32_e32 v190, 0xffff0000, v190
	v_lshlrev_b32_e32 v230, 16, v191
	v_and_b32_e32 v191, 0xffff0000, v191
	v_mul_f32_e32 v1, v120, v1
	v_and_b32_e32 v120, 0xffff0000, v192
	v_max_f32_e32 v190, v190, v190
	v_max_f32_e32 v191, v191, v191
	v_max_f32_e32 v120, v120, v120
	v_max_f32_e32 v230, v230, v230
	v_max_f32_e32 v190, 0x219392ef, v190
	v_max_f32_e32 v191, 0x219392ef, v191
	v_max_f32_e32 v120, 0x219392ef, v120
	v_max_f32_e32 v230, 0x219392ef, v230
	v_mul_f32_e32 v188, v125, v190
	v_mul_f32_e32 v127, v127, v191
	v_cvt_pk_bf16_f32 v125, v129, v130
	v_lshl_add_u64 v[128:129], s[78:79], 0, v[234:235]
	v_mul_f32_e32 v120, v121, v120
	v_mul_f32_e32 v189, v126, v230
	v_cvt_pk_bf16_f32 v126, v131, v188
	v_cvt_pk_bf16_f32 v127, v189, v127
	v_lshl_add_u64 v[128:129], v[128:129], 0, v[2:3]
	global_store_dwordx4 v[128:129], v[124:127], off
	s_nop 1
	v_cvt_pk_bf16_f32 v120, v1, v120
	v_lshlrev_b32_e32 v1, 16, v193
	v_and_b32_e32 v121, 0xffff0000, v193
	v_max_f32_e32 v1, v1, v1
	v_max_f32_e32 v121, v121, v121
	v_max_f32_e32 v1, 0x219392ef, v1
	v_max_f32_e32 v121, 0x219392ef, v121
	v_mul_f32_e32 v1, v122, v1
	v_mul_f32_e32 v121, v123, v121
	v_cvt_pk_bf16_f32 v121, v1, v121
	v_lshlrev_b32_e32 v1, 16, v194
	v_max_f32_e32 v1, v1, v1
	v_max_f32_e32 v1, 0x219392ef, v1
	v_mul_f32_e32 v1, v116, v1
	v_and_b32_e32 v116, 0xffff0000, v194
	v_max_f32_e32 v116, v116, v116
	v_max_f32_e32 v116, 0x219392ef, v116
	v_mul_f32_e32 v116, v117, v116
	v_cvt_pk_bf16_f32 v122, v1, v116
	v_lshlrev_b32_e32 v1, 16, v195
	v_max_f32_e32 v1, v1, v1
	v_and_b32_e32 v116, 0xffff0000, v195
	v_max_f32_e32 v1, 0x219392ef, v1
	v_max_f32_e32 v116, v116, v116
	v_mul_f32_e32 v1, v118, v1
	v_max_f32_e32 v116, 0x219392ef, v116
	v_mul_f32_e32 v116, v119, v116
	v_cvt_pk_bf16_f32 v123, v1, v116
	v_lshlrev_b32_e32 v1, 16, v214
	v_max_f32_e32 v1, v1, v1
	v_max_f32_e32 v1, 0x219392ef, v1
	v_mul_f32_e32 v1, v112, v1
	v_and_b32_e32 v112, 0xffff0000, v214
	v_max_f32_e32 v112, v112, v112
	v_max_f32_e32 v112, 0x219392ef, v112
	v_mul_f32_e32 v112, v113, v112
	v_lshl_add_u64 v[116:117], v[128:129], 0, s[6:7]
	global_store_dwordx4 v[116:117], v[120:123], off
	s_nop 1
	v_cvt_pk_bf16_f32 v112, v1, v112
	v_lshlrev_b32_e32 v1, 16, v215
	v_and_b32_e32 v113, 0xffff0000, v215
	v_max_f32_e32 v1, v1, v1
	v_max_f32_e32 v113, v113, v113
	v_max_f32_e32 v1, 0x219392ef, v1
	v_max_f32_e32 v113, 0x219392ef, v113
	v_mul_f32_e32 v1, v114, v1
	v_mul_f32_e32 v113, v115, v113
	v_cvt_pk_bf16_f32 v113, v1, v113
	v_lshlrev_b32_e32 v1, 16, v216
	v_max_f32_e32 v1, v1, v1
	v_max_f32_e32 v1, 0x219392ef, v1
	v_mul_f32_e32 v1, v108, v1
	v_and_b32_e32 v108, 0xffff0000, v216
	v_max_f32_e32 v108, v108, v108
	v_max_f32_e32 v108, 0x219392ef, v108
	v_mul_f32_e32 v108, v109, v108
	v_cvt_pk_bf16_f32 v114, v1, v108
	v_lshlrev_b32_e32 v1, 16, v217
	v_max_f32_e32 v1, v1, v1
	v_and_b32_e32 v108, 0xffff0000, v217
	v_max_f32_e32 v1, 0x219392ef, v1
	v_max_f32_e32 v108, v108, v108
	v_mul_f32_e32 v1, v110, v1
	v_max_f32_e32 v108, 0x219392ef, v108
	v_mul_f32_e32 v108, v111, v108
	v_cvt_pk_bf16_f32 v115, v1, v108
	v_lshlrev_b32_e32 v1, 16, v218
	v_max_f32_e32 v1, v1, v1
	v_max_f32_e32 v1, 0x219392ef, v1
	v_mul_f32_e32 v1, v104, v1
	v_and_b32_e32 v104, 0xffff0000, v218
	v_max_f32_e32 v104, v104, v104
	v_lshlrev_b64 v[108:109], 11, v[232:233]
	v_max_f32_e32 v104, 0x219392ef, v104
	v_lshl_add_u64 v[108:109], s[78:79], 0, v[108:109]
	v_mul_f32_e32 v104, v105, v104
	v_lshl_add_u64 v[108:109], v[108:109], 0, v[2:3]
	global_store_dwordx4 v[108:109], v[112:115], off
	s_nop 1
	v_cvt_pk_bf16_f32 v104, v1, v104
	v_lshlrev_b32_e32 v1, 16, v219
	v_and_b32_e32 v105, 0xffff0000, v219
	v_max_f32_e32 v1, v1, v1
	v_max_f32_e32 v105, v105, v105
	v_max_f32_e32 v1, 0x219392ef, v1
	v_max_f32_e32 v105, 0x219392ef, v105
	v_mul_f32_e32 v1, v106, v1
	v_mul_f32_e32 v105, v107, v105
	v_cvt_pk_bf16_f32 v105, v1, v105
	v_lshlrev_b32_e32 v1, 16, v220
	v_max_f32_e32 v1, v1, v1
	v_max_f32_e32 v1, 0x219392ef, v1
	v_mul_f32_e32 v1, v100, v1
	v_and_b32_e32 v100, 0xffff0000, v220
	v_max_f32_e32 v100, v100, v100
	v_max_f32_e32 v100, 0x219392ef, v100
	v_mul_f32_e32 v100, v101, v100
	v_cvt_pk_bf16_f32 v106, v1, v100
	v_lshlrev_b32_e32 v1, 16, v221
	v_max_f32_e32 v1, v1, v1
	v_and_b32_e32 v100, 0xffff0000, v221
	v_max_f32_e32 v1, 0x219392ef, v1
	v_max_f32_e32 v100, v100, v100
	v_mul_f32_e32 v1, v102, v1
	v_max_f32_e32 v100, 0x219392ef, v100
	v_mul_f32_e32 v100, v103, v100
	v_cvt_pk_bf16_f32 v107, v1, v100
	v_lshlrev_b32_e32 v1, 16, v226
	v_max_f32_e32 v1, v1, v1
	v_max_f32_e32 v1, 0x219392ef, v1
	v_mul_f32_e32 v1, v96, v1
	v_and_b32_e32 v96, 0xffff0000, v226
	v_max_f32_e32 v96, v96, v96
	v_max_f32_e32 v96, 0x219392ef, v96
	v_mul_f32_e32 v96, v97, v96
	v_lshl_add_u64 v[100:101], v[108:109], 0, s[6:7]
	global_store_dwordx4 v[100:101], v[104:107], off
	s_nop 1
	v_cvt_pk_bf16_f32 v96, v1, v96
	v_lshlrev_b32_e32 v1, 16, v227
	v_and_b32_e32 v97, 0xffff0000, v227
	v_max_f32_e32 v1, v1, v1
	v_max_f32_e32 v97, v97, v97
	v_max_f32_e32 v1, 0x219392ef, v1
	v_max_f32_e32 v97, 0x219392ef, v97
	v_mul_f32_e32 v1, v98, v1
	v_mul_f32_e32 v97, v99, v97
	v_cvt_pk_bf16_f32 v97, v1, v97
	v_lshlrev_b32_e32 v1, 16, v228
	v_max_f32_e32 v1, v1, v1
	v_max_f32_e32 v1, 0x219392ef, v1
	v_mul_f32_e32 v1, v92, v1
	v_and_b32_e32 v92, 0xffff0000, v228
	v_max_f32_e32 v92, v92, v92
	v_max_f32_e32 v92, 0x219392ef, v92
	v_mul_f32_e32 v92, v93, v92
	v_cvt_pk_bf16_f32 v98, v1, v92
	v_lshlrev_b32_e32 v1, 16, v229
	v_max_f32_e32 v1, v1, v1
	v_and_b32_e32 v92, 0xffff0000, v229
	v_max_f32_e32 v1, 0x219392ef, v1
	v_max_f32_e32 v92, v92, v92
	v_mul_f32_e32 v1, v94, v1
	v_max_f32_e32 v92, 0x219392ef, v92
	v_mul_f32_e32 v92, v95, v92
	v_cvt_pk_bf16_f32 v99, v1, v92
	v_lshlrev_b32_e32 v1, 16, v172
	v_max_f32_e32 v1, v1, v1
	v_max_f32_e32 v1, 0x219392ef, v1
	v_mul_f32_e32 v1, v88, v1
	v_and_b32_e32 v88, 0xffff0000, v172
	v_max_f32_e32 v88, v88, v88
	v_lshlrev_b64 v[92:93], 11, v[186:187]
	v_max_f32_e32 v88, 0x219392ef, v88
	v_lshl_add_u64 v[92:93], s[78:79], 0, v[92:93]
	v_mul_f32_e32 v88, v89, v88
	v_lshl_add_u64 v[92:93], v[92:93], 0, v[2:3]
	global_store_dwordx4 v[92:93], v[96:99], off
	s_nop 1
	v_cvt_pk_bf16_f32 v88, v1, v88
	v_lshlrev_b32_e32 v1, 16, v173
	v_and_b32_e32 v89, 0xffff0000, v173
	v_max_f32_e32 v1, v1, v1
	v_max_f32_e32 v89, v89, v89
	v_max_f32_e32 v1, 0x219392ef, v1
	v_max_f32_e32 v89, 0x219392ef, v89
	v_mul_f32_e32 v1, v90, v1
	v_mul_f32_e32 v89, v91, v89
	v_cvt_pk_bf16_f32 v89, v1, v89
	v_lshlrev_b32_e32 v1, 16, v174
	v_max_f32_e32 v1, v1, v1
	v_max_f32_e32 v1, 0x219392ef, v1
	v_mul_f32_e32 v1, v84, v1
	v_and_b32_e32 v84, 0xffff0000, v174
	v_max_f32_e32 v84, v84, v84
	v_max_f32_e32 v84, 0x219392ef, v84
	v_mul_f32_e32 v84, v85, v84
	v_cvt_pk_bf16_f32 v90, v1, v84
	v_lshlrev_b32_e32 v1, 16, v175
	v_max_f32_e32 v1, v1, v1
	v_and_b32_e32 v84, 0xffff0000, v175
	v_max_f32_e32 v1, 0x219392ef, v1
	v_max_f32_e32 v84, v84, v84
	v_mul_f32_e32 v1, v86, v1
	v_max_f32_e32 v84, 0x219392ef, v84
	v_mul_f32_e32 v84, v87, v84
	v_cvt_pk_bf16_f32 v91, v1, v84
	v_lshlrev_b32_e32 v1, 16, v168
	v_max_f32_e32 v1, v1, v1
	v_max_f32_e32 v1, 0x219392ef, v1
	v_mul_f32_e32 v1, v80, v1
	v_and_b32_e32 v80, 0xffff0000, v168
	v_max_f32_e32 v80, v80, v80
	v_max_f32_e32 v80, 0x219392ef, v80
	v_mul_f32_e32 v80, v81, v80
	v_lshl_add_u64 v[84:85], v[92:93], 0, s[6:7]
	global_store_dwordx4 v[84:85], v[88:91], off
	s_nop 1
	v_cvt_pk_bf16_f32 v80, v1, v80
	v_lshlrev_b32_e32 v1, 16, v169
	v_and_b32_e32 v81, 0xffff0000, v169
	v_max_f32_e32 v1, v1, v1
	v_max_f32_e32 v81, v81, v81
	v_max_f32_e32 v1, 0x219392ef, v1
	v_max_f32_e32 v81, 0x219392ef, v81
	v_mul_f32_e32 v1, v82, v1
	v_mul_f32_e32 v81, v83, v81
	v_cvt_pk_bf16_f32 v81, v1, v81
	v_lshlrev_b32_e32 v1, 16, v170
	v_max_f32_e32 v1, v1, v1
	v_max_f32_e32 v1, 0x219392ef, v1
	v_mul_f32_e32 v1, v76, v1
	v_and_b32_e32 v76, 0xffff0000, v170
	v_max_f32_e32 v76, v76, v76
	v_max_f32_e32 v76, 0x219392ef, v76
	v_mul_f32_e32 v76, v77, v76
	v_cvt_pk_bf16_f32 v82, v1, v76
	v_lshlrev_b32_e32 v1, 16, v171
	v_max_f32_e32 v1, v1, v1
	v_and_b32_e32 v76, 0xffff0000, v171
	v_max_f32_e32 v1, 0x219392ef, v1
	v_max_f32_e32 v76, v76, v76
	v_mul_f32_e32 v1, v78, v1
	v_max_f32_e32 v76, 0x219392ef, v76
	v_mul_f32_e32 v76, v79, v76
	v_cvt_pk_bf16_f32 v83, v1, v76
	v_lshlrev_b32_e32 v1, 16, v164
	v_max_f32_e32 v1, v1, v1
	v_max_f32_e32 v1, 0x219392ef, v1
	v_mul_f32_e32 v1, v72, v1
	v_and_b32_e32 v72, 0xffff0000, v164
	v_max_f32_e32 v72, v72, v72
	v_lshlrev_b64 v[76:77], 11, v[184:185]
	v_max_f32_e32 v72, 0x219392ef, v72
	v_lshl_add_u64 v[76:77], s[78:79], 0, v[76:77]
	v_mul_f32_e32 v72, v73, v72
	v_lshl_add_u64 v[76:77], v[76:77], 0, v[2:3]
	global_store_dwordx4 v[76:77], v[80:83], off
	s_nop 1
	v_cvt_pk_bf16_f32 v72, v1, v72
	v_lshlrev_b32_e32 v1, 16, v165
	v_and_b32_e32 v73, 0xffff0000, v165
	v_max_f32_e32 v1, v1, v1
	v_max_f32_e32 v73, v73, v73
	v_max_f32_e32 v1, 0x219392ef, v1
	v_max_f32_e32 v73, 0x219392ef, v73
	v_mul_f32_e32 v1, v74, v1
	v_mul_f32_e32 v73, v75, v73
	v_cvt_pk_bf16_f32 v73, v1, v73
	v_lshlrev_b32_e32 v1, 16, v166
	v_max_f32_e32 v1, v1, v1
	v_max_f32_e32 v1, 0x219392ef, v1
	v_mul_f32_e32 v1, v68, v1
	v_and_b32_e32 v68, 0xffff0000, v166
	v_max_f32_e32 v68, v68, v68
	v_max_f32_e32 v68, 0x219392ef, v68
	v_mul_f32_e32 v68, v69, v68
	v_cvt_pk_bf16_f32 v74, v1, v68
	v_lshlrev_b32_e32 v1, 16, v167
	v_max_f32_e32 v1, v1, v1
	v_and_b32_e32 v68, 0xffff0000, v167
	v_max_f32_e32 v1, 0x219392ef, v1
	v_max_f32_e32 v68, v68, v68
	v_mul_f32_e32 v1, v70, v1
	v_max_f32_e32 v68, 0x219392ef, v68
	v_mul_f32_e32 v68, v71, v68
	v_cvt_pk_bf16_f32 v75, v1, v68
	v_lshlrev_b32_e32 v1, 16, v160
	v_max_f32_e32 v1, v1, v1
	v_max_f32_e32 v1, 0x219392ef, v1
	v_mul_f32_e32 v1, v64, v1
	v_and_b32_e32 v64, 0xffff0000, v160
	v_max_f32_e32 v64, v64, v64
	v_max_f32_e32 v64, 0x219392ef, v64
	v_mul_f32_e32 v64, v65, v64
	v_lshl_add_u64 v[68:69], v[76:77], 0, s[6:7]
	global_store_dwordx4 v[68:69], v[72:75], off
	s_nop 1
	v_cvt_pk_bf16_f32 v64, v1, v64
	v_lshlrev_b32_e32 v1, 16, v161
	v_and_b32_e32 v65, 0xffff0000, v161
	v_max_f32_e32 v1, v1, v1
	v_max_f32_e32 v65, v65, v65
	v_max_f32_e32 v1, 0x219392ef, v1
	v_max_f32_e32 v65, 0x219392ef, v65
	v_mul_f32_e32 v1, v66, v1
	v_mul_f32_e32 v65, v67, v65
	v_cvt_pk_bf16_f32 v65, v1, v65
	v_lshlrev_b32_e32 v1, 16, v162
	v_max_f32_e32 v1, v1, v1
	v_max_f32_e32 v1, 0x219392ef, v1
	v_mul_f32_e32 v1, v60, v1
	v_and_b32_e32 v60, 0xffff0000, v162
	v_max_f32_e32 v60, v60, v60
	v_max_f32_e32 v60, 0x219392ef, v60
	v_mul_f32_e32 v60, v61, v60
	v_cvt_pk_bf16_f32 v66, v1, v60
	v_lshlrev_b32_e32 v1, 16, v163
	v_max_f32_e32 v1, v1, v1
	v_and_b32_e32 v60, 0xffff0000, v163
	v_max_f32_e32 v1, 0x219392ef, v1
	v_max_f32_e32 v60, v60, v60
	v_mul_f32_e32 v1, v62, v1
	v_max_f32_e32 v60, 0x219392ef, v60
	v_mul_f32_e32 v60, v63, v60
	v_cvt_pk_bf16_f32 v67, v1, v60
	v_lshlrev_b32_e32 v1, 16, v156
	v_max_f32_e32 v1, v1, v1
	v_max_f32_e32 v1, 0x219392ef, v1
	v_mul_f32_e32 v1, v56, v1
	v_and_b32_e32 v56, 0xffff0000, v156
	v_max_f32_e32 v56, v56, v56
	v_lshlrev_b64 v[60:61], 11, v[182:183]
	v_max_f32_e32 v56, 0x219392ef, v56
	v_lshl_add_u64 v[60:61], s[78:79], 0, v[60:61]
	v_mul_f32_e32 v56, v57, v56
	v_lshl_add_u64 v[60:61], v[60:61], 0, v[2:3]
	global_store_dwordx4 v[60:61], v[64:67], off
	s_nop 1
	v_cvt_pk_bf16_f32 v56, v1, v56
	v_lshlrev_b32_e32 v1, 16, v157
	v_and_b32_e32 v57, 0xffff0000, v157
	v_max_f32_e32 v1, v1, v1
	v_max_f32_e32 v57, v57, v57
	v_max_f32_e32 v1, 0x219392ef, v1
	v_max_f32_e32 v57, 0x219392ef, v57
	v_mul_f32_e32 v1, v58, v1
	v_mul_f32_e32 v57, v59, v57
	v_cvt_pk_bf16_f32 v57, v1, v57
	v_lshlrev_b32_e32 v1, 16, v158
	v_max_f32_e32 v1, v1, v1
	v_max_f32_e32 v1, 0x219392ef, v1
	v_mul_f32_e32 v1, v52, v1
	v_and_b32_e32 v52, 0xffff0000, v158
	v_max_f32_e32 v52, v52, v52
	v_max_f32_e32 v52, 0x219392ef, v52
	v_mul_f32_e32 v52, v53, v52
	v_cvt_pk_bf16_f32 v58, v1, v52
	v_lshlrev_b32_e32 v1, 16, v159
	v_max_f32_e32 v1, v1, v1
	v_and_b32_e32 v52, 0xffff0000, v159
	v_max_f32_e32 v1, 0x219392ef, v1
	v_max_f32_e32 v52, v52, v52
	v_mul_f32_e32 v1, v54, v1
	v_max_f32_e32 v52, 0x219392ef, v52
	v_mul_f32_e32 v52, v55, v52
	v_cvt_pk_bf16_f32 v59, v1, v52
	v_lshlrev_b32_e32 v1, 16, v152
	v_max_f32_e32 v1, v1, v1
	v_max_f32_e32 v1, 0x219392ef, v1
	v_mul_f32_e32 v1, v48, v1
	v_and_b32_e32 v48, 0xffff0000, v152
	v_max_f32_e32 v48, v48, v48
	v_max_f32_e32 v48, 0x219392ef, v48
	v_mul_f32_e32 v48, v49, v48
	v_lshl_add_u64 v[52:53], v[60:61], 0, s[6:7]
	global_store_dwordx4 v[52:53], v[56:59], off
	s_nop 1
	v_cvt_pk_bf16_f32 v48, v1, v48
	v_lshlrev_b32_e32 v1, 16, v153
	v_and_b32_e32 v49, 0xffff0000, v153
	v_max_f32_e32 v1, v1, v1
	v_max_f32_e32 v49, v49, v49
	v_max_f32_e32 v1, 0x219392ef, v1
	v_max_f32_e32 v49, 0x219392ef, v49
	v_mul_f32_e32 v1, v50, v1
	v_mul_f32_e32 v49, v51, v49
	v_cvt_pk_bf16_f32 v49, v1, v49
	v_lshlrev_b32_e32 v1, 16, v154
	v_max_f32_e32 v1, v1, v1
	v_max_f32_e32 v1, 0x219392ef, v1
	v_mul_f32_e32 v1, v44, v1
	v_and_b32_e32 v44, 0xffff0000, v154
	v_max_f32_e32 v44, v44, v44
	v_max_f32_e32 v44, 0x219392ef, v44
	v_mul_f32_e32 v44, v45, v44
	v_cvt_pk_bf16_f32 v50, v1, v44
	v_lshlrev_b32_e32 v1, 16, v155
	v_max_f32_e32 v1, v1, v1
	v_and_b32_e32 v44, 0xffff0000, v155
	v_max_f32_e32 v1, 0x219392ef, v1
	v_max_f32_e32 v44, v44, v44
	v_mul_f32_e32 v1, v46, v1
	v_max_f32_e32 v44, 0x219392ef, v44
	v_mul_f32_e32 v44, v47, v44
	v_cvt_pk_bf16_f32 v51, v1, v44
	v_lshlrev_b32_e32 v1, 16, v148
	v_max_f32_e32 v1, v1, v1
	v_max_f32_e32 v1, 0x219392ef, v1
	v_mul_f32_e32 v1, v40, v1
	v_and_b32_e32 v40, 0xffff0000, v148
	v_max_f32_e32 v40, v40, v40
	v_lshlrev_b64 v[44:45], 11, v[180:181]
	v_max_f32_e32 v40, 0x219392ef, v40
	v_lshl_add_u64 v[44:45], s[78:79], 0, v[44:45]
	v_mul_f32_e32 v40, v41, v40
	v_lshl_add_u64 v[44:45], v[44:45], 0, v[2:3]
	global_store_dwordx4 v[44:45], v[48:51], off
	s_nop 1
	v_cvt_pk_bf16_f32 v40, v1, v40
	v_lshlrev_b32_e32 v1, 16, v149
	v_and_b32_e32 v41, 0xffff0000, v149
	v_max_f32_e32 v1, v1, v1
	v_max_f32_e32 v41, v41, v41
	v_max_f32_e32 v1, 0x219392ef, v1
	v_max_f32_e32 v41, 0x219392ef, v41
	v_mul_f32_e32 v1, v42, v1
	v_mul_f32_e32 v41, v43, v41
	v_cvt_pk_bf16_f32 v41, v1, v41
	v_lshlrev_b32_e32 v1, 16, v150
	v_max_f32_e32 v1, v1, v1
	v_max_f32_e32 v1, 0x219392ef, v1
	v_mul_f32_e32 v1, v36, v1
	v_and_b32_e32 v36, 0xffff0000, v150
	v_max_f32_e32 v36, v36, v36
	v_max_f32_e32 v36, 0x219392ef, v36
	v_mul_f32_e32 v36, v37, v36
	v_cvt_pk_bf16_f32 v42, v1, v36
	v_lshlrev_b32_e32 v1, 16, v151
	v_max_f32_e32 v1, v1, v1
	v_and_b32_e32 v36, 0xffff0000, v151
	v_max_f32_e32 v1, 0x219392ef, v1
	v_max_f32_e32 v36, v36, v36
	v_mul_f32_e32 v1, v38, v1
	v_max_f32_e32 v36, 0x219392ef, v36
	v_mul_f32_e32 v36, v39, v36
	v_cvt_pk_bf16_f32 v43, v1, v36
	v_lshlrev_b32_e32 v1, 16, v144
	v_max_f32_e32 v1, v1, v1
	v_max_f32_e32 v1, 0x219392ef, v1
	v_mul_f32_e32 v1, v32, v1
	v_and_b32_e32 v32, 0xffff0000, v144
	v_max_f32_e32 v32, v32, v32
	v_max_f32_e32 v32, 0x219392ef, v32
	v_mul_f32_e32 v32, v33, v32
	v_lshl_add_u64 v[36:37], v[44:45], 0, s[6:7]
	global_store_dwordx4 v[36:37], v[40:43], off
	s_nop 1
	v_cvt_pk_bf16_f32 v32, v1, v32
	v_lshlrev_b32_e32 v1, 16, v145
	v_and_b32_e32 v33, 0xffff0000, v145
	v_max_f32_e32 v1, v1, v1
	v_max_f32_e32 v33, v33, v33
	v_max_f32_e32 v1, 0x219392ef, v1
	v_max_f32_e32 v33, 0x219392ef, v33
	v_mul_f32_e32 v1, v34, v1
	v_mul_f32_e32 v33, v35, v33
	v_cvt_pk_bf16_f32 v33, v1, v33
	v_lshlrev_b32_e32 v1, 16, v146
	v_max_f32_e32 v1, v1, v1
	v_max_f32_e32 v1, 0x219392ef, v1
	v_mul_f32_e32 v1, v28, v1
	v_and_b32_e32 v28, 0xffff0000, v146
	v_max_f32_e32 v28, v28, v28
	v_max_f32_e32 v28, 0x219392ef, v28
	v_mul_f32_e32 v28, v29, v28
	v_cvt_pk_bf16_f32 v34, v1, v28
	v_lshlrev_b32_e32 v1, 16, v147
	v_max_f32_e32 v1, v1, v1
	v_and_b32_e32 v28, 0xffff0000, v147
	v_max_f32_e32 v1, 0x219392ef, v1
	v_max_f32_e32 v28, v28, v28
	v_mul_f32_e32 v1, v30, v1
	v_max_f32_e32 v28, 0x219392ef, v28
	v_mul_f32_e32 v28, v31, v28
	v_cvt_pk_bf16_f32 v35, v1, v28
	v_lshlrev_b32_e32 v1, 16, v140
	v_max_f32_e32 v1, v1, v1
	v_max_f32_e32 v1, 0x219392ef, v1
	v_mul_f32_e32 v1, v24, v1
	v_and_b32_e32 v24, 0xffff0000, v140
	v_max_f32_e32 v24, v24, v24
	v_lshlrev_b64 v[28:29], 11, v[178:179]
	v_max_f32_e32 v24, 0x219392ef, v24
	v_lshl_add_u64 v[28:29], s[78:79], 0, v[28:29]
	v_mul_f32_e32 v24, v25, v24
	v_lshl_add_u64 v[28:29], v[28:29], 0, v[2:3]
	global_store_dwordx4 v[28:29], v[32:35], off
	s_nop 1
	v_cvt_pk_bf16_f32 v24, v1, v24
	v_lshlrev_b32_e32 v1, 16, v141
	v_and_b32_e32 v25, 0xffff0000, v141
	v_max_f32_e32 v1, v1, v1
	v_max_f32_e32 v25, v25, v25
	v_max_f32_e32 v1, 0x219392ef, v1
	v_max_f32_e32 v25, 0x219392ef, v25
	v_mul_f32_e32 v1, v26, v1
	v_mul_f32_e32 v25, v27, v25
	v_cvt_pk_bf16_f32 v25, v1, v25
	v_lshlrev_b32_e32 v1, 16, v142
	v_max_f32_e32 v1, v1, v1
	v_max_f32_e32 v1, 0x219392ef, v1
	v_mul_f32_e32 v1, v20, v1
	v_and_b32_e32 v20, 0xffff0000, v142
	v_max_f32_e32 v20, v20, v20
	v_max_f32_e32 v20, 0x219392ef, v20
	v_mul_f32_e32 v20, v21, v20
	v_cvt_pk_bf16_f32 v26, v1, v20
	v_lshlrev_b32_e32 v1, 16, v143
	v_max_f32_e32 v1, v1, v1
	v_and_b32_e32 v20, 0xffff0000, v143
	v_max_f32_e32 v1, 0x219392ef, v1
	v_max_f32_e32 v20, v20, v20
	v_mul_f32_e32 v1, v22, v1
	v_max_f32_e32 v20, 0x219392ef, v20
	v_mul_f32_e32 v20, v23, v20
	v_cvt_pk_bf16_f32 v27, v1, v20
	v_lshlrev_b32_e32 v1, 16, v136
	v_max_f32_e32 v1, v1, v1
	v_max_f32_e32 v1, 0x219392ef, v1
	v_mul_f32_e32 v1, v16, v1
	v_and_b32_e32 v16, 0xffff0000, v136
	v_max_f32_e32 v16, v16, v16
	v_max_f32_e32 v16, 0x219392ef, v16
	v_mul_f32_e32 v16, v17, v16
	v_lshl_add_u64 v[20:21], v[28:29], 0, s[6:7]
	global_store_dwordx4 v[20:21], v[24:27], off
	s_nop 1
	v_cvt_pk_bf16_f32 v16, v1, v16
	v_lshlrev_b32_e32 v1, 16, v137
	v_and_b32_e32 v17, 0xffff0000, v137
	v_max_f32_e32 v1, v1, v1
	v_max_f32_e32 v17, v17, v17
	v_max_f32_e32 v1, 0x219392ef, v1
	v_max_f32_e32 v17, 0x219392ef, v17
	v_mul_f32_e32 v1, v18, v1
	v_mul_f32_e32 v17, v19, v17
	v_cvt_pk_bf16_f32 v17, v1, v17
	v_lshlrev_b32_e32 v1, 16, v138
	v_max_f32_e32 v1, v1, v1
	v_max_f32_e32 v1, 0x219392ef, v1
	v_mul_f32_e32 v1, v12, v1
	v_and_b32_e32 v12, 0xffff0000, v138
	v_max_f32_e32 v12, v12, v12
	v_max_f32_e32 v12, 0x219392ef, v12
	v_mul_f32_e32 v12, v13, v12
	v_cvt_pk_bf16_f32 v18, v1, v12
	v_and_b32_e32 v12, 0xffff0000, v139
	v_lshlrev_b32_e32 v1, 16, v139
	v_max_f32_e32 v12, v12, v12
	v_max_f32_e32 v1, v1, v1
	v_max_f32_e32 v12, 0x219392ef, v12
	v_max_f32_e32 v1, 0x219392ef, v1
	v_mul_f32_e32 v12, v15, v12
	v_mul_f32_e32 v1, v14, v1
	v_cvt_pk_bf16_f32 v19, v1, v12
	v_lshlrev_b64 v[12:13], 11, v[176:177]
	v_lshl_add_u64 v[12:13], s[78:79], 0, v[12:13]
	v_lshl_add_u64 v[12:13], v[12:13], 0, v[2:3]
	v_lshlrev_b32_e32 v1, 16, v132
	v_and_b32_e32 v2, 0xffff0000, v132
	v_max_f32_e32 v1, v1, v1
	v_max_f32_e32 v2, v2, v2
	v_max_f32_e32 v1, 0x219392ef, v1
	v_max_f32_e32 v2, 0x219392ef, v2
	v_mul_f32_e32 v1, v8, v1
	v_mul_f32_e32 v2, v9, v2
	global_store_dwordx4 v[12:13], v[16:19], off
	s_nop 1
	v_cvt_pk_bf16_f32 v2, v1, v2
	v_lshlrev_b32_e32 v1, 16, v133
	v_and_b32_e32 v3, 0xffff0000, v133
	v_max_f32_e32 v1, v1, v1
	v_max_f32_e32 v3, v3, v3
	v_max_f32_e32 v1, 0x219392ef, v1
	v_max_f32_e32 v3, 0x219392ef, v3
	v_mul_f32_e32 v1, v10, v1
	v_mul_f32_e32 v3, v11, v3
	v_cvt_pk_bf16_f32 v3, v1, v3
	v_lshlrev_b32_e32 v1, 16, v134
	v_max_f32_e32 v1, v1, v1
	v_max_f32_e32 v1, 0x219392ef, v1
	v_mul_f32_e32 v1, v4, v1
	v_and_b32_e32 v4, 0xffff0000, v134
	v_max_f32_e32 v4, v4, v4
	v_max_f32_e32 v4, 0x219392ef, v4
	v_mul_f32_e32 v4, v5, v4
	v_and_b32_e32 v5, 0xffff0000, v135
	v_cvt_pk_bf16_f32 v4, v1, v4
	v_lshlrev_b32_e32 v1, 16, v135
	v_max_f32_e32 v5, v5, v5
	v_max_f32_e32 v1, v1, v1
	v_max_f32_e32 v5, 0x219392ef, v5
	v_max_f32_e32 v1, 0x219392ef, v1
	v_mul_f32_e32 v5, v7, v5
	v_mul_f32_e32 v1, v6, v1
	v_cvt_pk_bf16_f32 v5, v1, v5
	v_lshl_add_u64 v[6:7], v[12:13], 0, s[6:7]
	global_store_dwordx4 v[6:7], v[2:5], off
	s_nop 1
	s_cbranch_vccnz .LBB0_538

.LBB0_541:
.LBB0_591:
	s_cmp_lt_i32 s98, 5
	s_cselect_b64 s[0:1], -1, 0
	s_cmp_gt_i32 s99, 4
	s_cselect_b64 s[2:3], -1, 0
	s_and_b64 s[0:1], s[0:1], s[2:3]
	s_andn2_b64 vcc, exec, s[0:1]
	s_cbranch_vccnz .LBB0_653
	v_mov_b32_e32 v0, 0
	global_load_dword v161, v0, s[66:67] sc1
	v_mov_b32_e32 v0, 0x4000
	global_load_dword v171, v0, s[66:67] offset:512 sc1
	s_cmpk_gt_i32 s72, 0xff
	s_cbranch_scc1 .LBB0_653
	s_ashr_i32 s27, s72, 31
	s_lshr_b32 s0, s27, 29
	s_add_i32 s4, s72, s0
	s_and_b32 s0, s4, -8
	s_sub_i32 s3, s72, s0
	s_cmp_gt_i32 s3, -1
	s_cbranch_scc0 .LBB0_595
	s_lshl_b32 s2, s3, 5
	s_ashr_i32 s0, s4, 3
	s_cbranch_execz .LBB0_596
	s_branch .LBB0_597

.LBB0_597:
	v_add_u32_e32 v0, s33, v246
	v_ashrrev_i32_e32 v1, 31, v0
	v_lshrrev_b32_e32 v1, 22, v1
	v_add_u32_e32 v1, v0, v1
	v_ashrrev_i32_e32 v8, 10, v1
	v_mul_i32_i24_e32 v1, 0x400, v8
	v_sub_u32_e32 v1, v0, v1
	v_lshrrev_b32_e32 v2, 4, v1
	v_bitop3_b32 v1, v2, v1, 32 bitop3:0x6c
	v_ashrrev_i32_e32 v3, 31, v1
	v_lshrrev_b32_e32 v3, 26, v3
	v_add_u32_e32 v3, v1, v3
	v_ashrrev_i32_e32 v9, 6, v3
	v_and_b32_e32 v3, 0xc0, v3
	v_sub_u32_e32 v1, v1, v3
	v_mov_b32_e32 v3, 1
	v_lshlrev_b32_e32 v2, 3, v8
	v_lshlrev_b32_e32 v4, 5, v8
	v_ashrrev_i16_sdwa v1, v3, sext(v1) dst_sel:DWORD dst_unused:UNUSED_PAD src0_sel:DWORD src1_sel:BYTE_0
	v_and_b32_e32 v2, 0x1ffff0, v2
	v_and_b32_e32 v4, 32, v4
	s_waitcnt vmcnt(0)
	v_bfe_i32 v10, v1, 0, 16
	v_add_u32_e32 v1, v4, v10
	v_add_lshl_u32 v2, v9, v2, 11
	v_add_u32_e32 v0, 0x2000, v0
	v_lshl_add_u32 v128, v1, 1, v2
	v_ashrrev_i32_e32 v1, 31, v0
	v_lshrrev_b32_e32 v1, 22, v1
	s_add_i32 s0, s2, s0
	v_add_u32_e32 v1, v0, v1
	s_ashr_i32 s1, s0, 31
	v_ashrrev_i32_e32 v11, 10, v1
	s_lshr_b32 s1, s1, 27
	v_mul_i32_i24_e32 v1, 0x400, v11
	s_add_i32 s1, s0, s1
	v_sub_u32_e32 v0, v0, v1
	s_ashr_i32 s2, s1, 5
	s_and_b32 s1, s1, 0xffe0
	v_lshrrev_b32_e32 v1, 4, v0
	s_sub_i32 s1, s0, s1
	v_bitop3_b32 v0, v1, v0, 32 bitop3:0x6c
	s_bfe_i32 s0, s1, 0x80000
	v_ashrrev_i32_e32 v2, 31, v0
	s_bfe_u32 s0, s0, 0x3000c
	v_lshrrev_b32_e32 v2, 26, v2
	s_add_i32 s3, s1, s0
	v_add_u32_e32 v2, v0, v2
	s_bfe_i32 s0, s3, 0x80000
	s_and_b32 s3, s3, 0xf8
	v_ashrrev_i32_e32 v12, 6, v2
	v_and_b32_e32 v2, 0xffc0, v2
	s_sub_i32 s1, s1, s3
	v_sub_u32_e32 v0, v0, v2
	s_lshl_b32 s2, s2, 3
	s_sext_i32_i16 s0, s0
	s_sext_i32_i8 s1, s1
	v_lshrrev_b16_e32 v2, 7, v0
	s_lshr_b32 s0, s0, 3
	s_add_i32 s6, s2, s1
	v_and_b32_e32 v2, 1, v2
	s_ashr_i32 s7, s6, 31
	s_bfe_i64 s[4:5], s[0:1], 0x100000
	v_add_u16_e32 v0, v0, v2
	s_ashr_i32 s9, s63, 2
	s_lshl_b64 s[2:3], s[6:7], 19
	s_lshl_b64 s[4:5], s[4:5], 19
	v_lshlrev_b32_e32 v1, 3, v11
	v_lshlrev_b32_e32 v4, 5, v11
	v_ashrrev_i16_sdwa v0, v3, sext(v0) dst_sel:DWORD dst_unused:UNUSED_PAD src0_sel:DWORD src1_sel:BYTE_0
	s_add_u32 s20, s90, s4
	v_and_b32_e32 v1, 0x1ffff0, v1
	v_and_b32_e32 v4, 32, v4
	v_bfe_i32 v13, v0, 0, 16
	s_addc_u32 s21, s91, s5
	s_add_i32 m0, s76, 0x10000
	v_add_u32_e32 v0, v4, v13
	v_add_lshl_u32 v1, v12, v1, 11
	global_load_lds_dwordx4 v128, s[20:21]
	s_add_i32 m0, s76, 0x12000
	v_lshl_add_u32 v130, v0, 1, v1
	s_add_u32 s4, s20, 0x40000
	global_load_lds_dwordx4 v130, s[20:21]
	s_addc_u32 s5, s21, 0
	s_add_i32 m0, s76, 0x14000
	v_mov_b32_e32 v129, 0
	global_load_lds_dwordx4 v128, s[4:5]
	s_add_i32 m0, s76, 0x16000
	s_add_u32 s2, s78, s2
	s_addc_u32 s3, s79, s3
	s_cmp_lg_u32 s63, 0
	s_cbranch_scc1 .Lph_join
	s_mov_b64 exec, 1
	v_readlane_b32 s34, v254, 8
	s_lshl_b32 s36, s6, 8
	s_and_b32 s34, s34, 7
	s_mul_i32 s34, s34, 3
	s_add_u32 s34, s34, 3
	s_lshl_b32 s35, 1, s34
	s_add_u32 s35, s35, 1
	s_add_u32 s36, s36, 0x8040
	v_mov_b32_e32 v14, s36
	v_mov_b32_e32 v15, s35
	global_atomic_add v14, v15, s[66:67]
	s_lshl_b32 s38, s6, 9
	s_sub_u32 s38, s38, 0x4000
	s_add_u32 s38, s38, 0x8040
	s_add_u32 s39, s38, 0x100
	s_cmp_ge_u32 s6, 32
	s_cselect_b32 s38, s38, s36
	s_cselect_b32 s39, s39, s36
	v_mov_b32_e32 v16, s38
	v_mov_b32_e32 v17, s39
	s_mov_b32 s37, 0
.Lph_poll:
	global_load_dword v18, v14, s[66:67] sc1
	global_load_dword v19, v16, s[66:67] sc1
	global_load_dword v20, v17, s[66:67] sc1
	s_waitcnt vmcnt(0)
	v_readfirstlane_b32 s40, v18
	v_readfirstlane_b32 s41, v19
	v_readfirstlane_b32 s42, v20
	s_and_b32 s43, s40, 7
	s_and_b32 s41, s41, 7
	s_and_b32 s42, s42, 7
	s_xor_b32 s43, s43, 4
	s_xor_b32 s41, s41, 4
	s_xor_b32 s42, s42, 4
	s_or_b32 s43, s43, s41
	s_or_b32 s43, s43, s42
	s_cmp_eq_u32 s43, 0
	s_cbranch_scc1 .Lph_arrived
	s_sleep 1
	s_add_u32 s37, s37, 1
	s_cmp_lt_u32 s37, 0x40000
	s_cbranch_scc1 .Lph_poll
.Lph_arrived:
	s_lshr_b32 s40, s40, s34
	s_and_b32 s40, s40, 7
	s_cmp_eq_u32 s40, 4
	s_cbranch_scc1 .Lph_fast
	buffer_wbl2 sc1
	s_waitcnt vmcnt(0)
	v_add_u32_e32 v14, 4, v14
	v_mov_b32_e32 v15, 1
	global_atomic_add v14, v15, s[66:67]
	s_mov_b32 s37, 0
.Lph_poll2:
	global_load_dword v18, v14, s[66:67] sc1
	s_waitcnt vmcnt(0)
	v_readfirstlane_b32 s40, v18
	s_cmp_ge_u32 s40, 4
	s_cbranch_scc1 .Lph_fast
	s_sleep 1
	s_add_u32 s37, s37, 1
	s_cmp_lt_u32 s37, 0x40000
	s_cbranch_scc1 .Lph_poll2
.Lph_fast:
	buffer_inv sc1
	s_waitcnt vmcnt(0)
	s_mov_b64 exec, -1
.Lph_join:
	s_barrier
	s_add_i32 s28, s76, 0x2000
	global_load_lds_dwordx4 v130, s[4:5]
	s_mov_b32 m0, s76
	s_add_u32 s4, s2, 0x40000
	global_load_lds_dwordx4 v128, s[2:3]
	s_mov_b32 m0, s28
	s_addc_u32 s5, s3, 0
	s_add_i32 s29, s76, 0x4000
	global_load_lds_dwordx4 v130, s[2:3]
	s_mov_b32 m0, s29
	s_add_i32 s30, s76, 0x6000
	global_load_lds_dwordx4 v128, s[4:5]
	s_mov_b32 m0, s30
	v_mov_b32_e32 v131, v129
	global_load_lds_dwordx4 v130, s[4:5]
	v_lshl_add_u64 v[6:7], s[20:21], 0, v[128:129]
	v_lshl_add_u64 v[4:5], s[20:21], 0, v[130:131]
	v_lshl_add_u64 v[2:3], s[2:3], 0, v[128:129]
	s_cmp_lg_u32 s9, 1
	v_lshl_add_u64 v[0:1], s[2:3], 0, v[130:131]
	s_cbranch_scc1 .LBB0_599
	s_barrier
